# speedup vs baseline: 1.0180x; 1.0082x over previous
; __device__ __forceinline__ void finishSM(f32x16& p0, f32x16& p1, float alpha, float& l_reg, bf16x8& pa0, bf16x8& pa1, bf16x8& pa2, bf16x8& pa3) {
; #pragma unroll
;   for (int r = 0; r < 16; ++r) p1[r] = __builtin_amdgcn_exp2f(p1[r]);
;   float ps = 0;
; #pragma unroll
;   for (int r = 0; r < 16; ++r) ps += p0[r];
; #pragma unroll
;   for (int r = 0; r < 16; ++r) ps += p1[r];
;   { auto rr = __builtin_amdgcn_permlane32_swap(__float_as_uint(ps), __float_as_uint(ps), false, false);
;     ps = __uint_as_float(rr[0]) + __uint_as_float(rr[1]); }
;   l_reg = l_reg * alpha + ps;
;     ...
;   PK4(p0, 0, pa0); PK4(p0, 8, pa1); PK4(p1, 0, pa2); PK4(p1, 8, pa3);
;     ...
; }
; template <int BUFOFF>
; __device__ __forceinline__ void qkt_mla(f32x16& p0, f32x16& p1, const int* ka, const bf16x8* qr, const char* qlds) {
;   typedef __attribute__((address_space(3))) const bf16x8* lp;
;   p0 = f32x16{}; p1 = f32x16{};
; #pragma unroll
;   for (int d0 = 0; d0 < 12; ++d0) {
;     const int a = ka[d0 & 3] + (d0 >> 2) * 128 + BUFOFF;
;     const bf16x8 b0 = *(lp)(a), b1 = *(lp)(a + 12288);
;     bf16x8 qf;
;     qf = qr[d0];
;     p0 = __builtin_amdgcn_mfma_f32_32x32x16_bf16(b0, qf, p0, 0, 0, 0);
;     p1 = __builtin_amdgcn_mfma_f32_32x32x16_bf16(b1, qf, p1, 0, 0, 0);
;   }
; }
.LBB0_115:
	s_mov_b32 s55, s43
	s_mov_b32 s43, s52
	ds_read_b128 v[64:67], v169 offset:24576
	ds_read_b128 v[68:71], v169 offset:36864
	ds_read_b128 v[214:217], v190 offset:24576
	ds_read_b128 v[218:221], v190 offset:36864
	s_waitcnt lgkmcnt(0)
	v_mfma_f32_32x32x16_bf16 v[80:95], v[64:67], v[140:143], v[226:241]
	v_add_f32_e32 v144, v200, v145
	v_mfma_f32_32x32x16_bf16 v[64:79], v[68:71], v[140:143], v[226:241]
	v_add_f32_e32 v243, v203, v210
	v_add_f32_e32 v244, v202, v208
	v_add_f32_e32 v245, v205, v212
	v_add_f32_e32 v246, v199, v211
	v_add_f32_e32 v247, v201, v213
	v_mfma_f32_32x32x16_bf16 v[80:95], v[214:217], v[136:139], v[80:95]
	v_add_f32_e32 v251, v204, v207
	v_add_f32_e32 v252, v206, v209
	v_mov_b32_e32 v196, v158
	v_add_f32_e32 v144, v172, v144
	v_add_f32_e32 v243, v173, v243
	v_mfma_f32_32x32x16_bf16 v[64:79], v[218:221], v[136:139], v[64:79]
	ds_read_b128 v[214:217], v193 offset:24576
	ds_read_b128 v[218:221], v193 offset:36864
	v_add_f32_e32 v244, v170, v244
	v_add_f32_e32 v245, v171, v245
	v_add_f32_e32 v246, v196, v246
	v_mov_b32_e32 v222, v147
	v_mov_b32_e32 v223, v154
	v_mov_b32_e32 v224, v155
	s_waitcnt lgkmcnt(0)
	v_mfma_f32_32x32x16_bf16 v[80:95], v[214:217], v[132:135], v[80:95]
	v_mfma_f32_32x32x16_bf16 v[64:79], v[218:221], v[132:135], v[64:79]
	ds_read_b128 v[214:217], v192 offset:24576
	ds_read_b128 v[218:221], v192 offset:36864
	s_waitcnt lgkmcnt(0)
	v_mfma_f32_32x32x16_bf16 v[80:95], v[214:217], v[128:131], v[80:95]
	v_mfma_f32_32x32x16_bf16 v[64:79], v[218:221], v[128:131], v[64:79]
	ds_read_b128 v[214:217], v169 offset:24704
	ds_read_b128 v[218:221], v169 offset:36992
	s_waitcnt lgkmcnt(0)
	v_mfma_f32_32x32x16_bf16 v[80:95], v[214:217], v[124:127], v[80:95]
	v_mfma_f32_32x32x16_bf16 v[64:79], v[218:221], v[124:127], v[64:79]
	ds_read_b128 v[214:217], v190 offset:24704
	ds_read_b128 v[218:221], v190 offset:36992
	s_waitcnt lgkmcnt(0)
	v_mfma_f32_32x32x16_bf16 v[80:95], v[214:217], v[120:123], v[80:95]
	v_mfma_f32_32x32x16_bf16 v[64:79], v[218:221], v[120:123], v[64:79]
	ds_read_b128 v[214:217], v193 offset:24704
	ds_read_b128 v[218:221], v193 offset:36992
	s_waitcnt lgkmcnt(0)
	v_mfma_f32_32x32x16_bf16 v[80:95], v[214:217], v[116:119], v[80:95]
	v_mfma_f32_32x32x16_bf16 v[64:79], v[218:221], v[116:119], v[64:79]
	ds_read_b128 v[214:217], v192 offset:24704
	ds_read_b128 v[218:221], v192 offset:36992
	s_waitcnt lgkmcnt(0)
	v_mfma_f32_32x32x16_bf16 v[80:95], v[214:217], v[112:115], v[80:95]
	v_mfma_f32_32x32x16_bf16 v[64:79], v[218:221], v[112:115], v[64:79]
	ds_read_b128 v[214:217], v169 offset:24832
	ds_read_b128 v[218:221], v169 offset:37120
	s_waitcnt lgkmcnt(0)
	v_mfma_f32_32x32x16_bf16 v[80:95], v[214:217], v[108:111], v[80:95]
	v_mfma_f32_32x32x16_bf16 v[64:79], v[218:221], v[108:111], v[64:79]
	ds_read_b128 v[214:217], v190 offset:24832
	ds_read_b128 v[218:221], v190 offset:37120
	s_waitcnt lgkmcnt(0)
	v_mfma_f32_32x32x16_bf16 v[80:95], v[214:217], v[104:107], v[80:95]
	v_mfma_f32_32x32x16_bf16 v[64:79], v[218:221], v[104:107], v[64:79]
	ds_read_b128 v[214:217], v193 offset:24832
	ds_read_b128 v[218:221], v193 offset:37120
	s_waitcnt lgkmcnt(0)
	v_mfma_f32_32x32x16_bf16 v[80:95], v[214:217], v[100:103], v[80:95]
	v_mfma_f32_32x32x16_bf16 v[64:79], v[218:221], v[100:103], v[64:79]
	ds_read_b128 v[214:217], v192 offset:24832
	ds_read_b128 v[218:221], v192 offset:37120
	s_waitcnt lgkmcnt(0)
	v_mfma_f32_32x32x16_bf16 v[80:95], v[214:217], v[96:99], v[80:95]
	v_mov_b32_e32 v214, v159
	v_mov_b32_e32 v215, v152
	v_mov_b32_e32 v216, v153
	v_mov_b32_e32 v217, v150
	v_add_f32_e32 v247, v214, v247
	v_add_f32_e32 v251, v215, v251
	v_add_f32_e32 v252, v216, v252
	v_mfma_f32_32x32x16_bf16 v[64:79], v[218:221], v[96:99], v[64:79]
	v_mov_b32_e32 v218, v151
	v_mov_b32_e32 v219, v148
	v_mov_b32_e32 v220, v149
	v_mov_b32_e32 v221, v146
	v_add_f32_e32 v144, v217, v144
	v_add_f32_e32 v243, v218, v243
	v_add_f32_e32 v244, v219, v244
	v_add_f32_e32 v245, v220, v245
	v_add_f32_e32 v246, v221, v246
	v_add_f32_e32 v247, v222, v247
	v_add_f32_e32 v251, v223, v251
	v_add_f32_e32 v252, v224, v252
	v_add_f32_e32 v144, v144, v243
	v_add_f32_e32 v244, v244, v245
	v_add_f32_e32 v246, v246, v247
	v_add_f32_e32 v251, v251, v252
	v_add_f32_e32 v144, v144, v244
	v_add_f32_e32 v246, v246, v251
	v_add_f32_e32 v158, v144, v246
	v_mov_b32_e32 v159, v158
	v_cvt_pk_bf16_f32 v144, v145, v210
	v_cvt_pk_bf16_f32 v145, v208, v212
	v_cvt_pk_bf16_f32 v146, v211, v213
	v_cvt_pk_bf16_f32 v147, v207, v209
	v_cvt_pk_bf16_f32 v148, v200, v203
	v_cvt_pk_bf16_f32 v149, v202, v205
	v_cvt_pk_bf16_f32 v150, v199, v201
	v_cvt_pk_bf16_f32 v151, v204, v206
	v_cvt_pk_bf16_f32 v152, v172, v173
	v_cvt_pk_bf16_f32 v153, v170, v171
	v_cvt_pk_bf16_f32 v154, v196, v214
	s_nop 1
	v_permlane32_swap_b32_e32 v158, v159
	v_cvt_pk_bf16_f32 v155, v215, v216
	v_cvt_pk_bf16_f32 v170, v217, v218
	v_cvt_pk_bf16_f32 v171, v219, v220
	v_cvt_pk_bf16_f32 v172, v221, v222
	v_cvt_pk_bf16_f32 v173, v223, v224
	v_readlane_b32 s58, v249, 37
	v_readlane_b32 s59, v249, 38
	s_add_u32 s56, s58, s47
	s_addc_u32 s57, s59, s50
	s_add_u32 s4, s56, 0x17060000
	s_addc_u32 s5, s57, 0
	s_add_u32 s58, s58, s14
	s_addc_u32 s59, s59, s15
	s_add_u32 s60, s58, 0x1a040000
	s_mov_b32 m0, s41
	s_addc_u32 s61, s59, 0
	s_lshl_b32 s52, s54, 14
	s_add_i32 s62, s40, s52
	global_load_lds_dwordx4 v188, s[4:5]
	s_mov_b32 m0, s42
	s_nop 0
	global_load_lds_dwordx4 v189, s[4:5]
	s_add_i32 m0, s41, 0x4000
	s_nop 0
	global_load_lds_dwordx4 v191, s[4:5]
	s_mov_b32 m0, s62
	s_nop 0
	global_load_lds_dwordx4 v194, s[60:61]
	s_add_i32 m0, s62, 0x2000
	s_nop 0
	global_load_lds_dwordx4 v195, s[60:61]
	s_lshl_b32 s60, s43, 14
	v_add_u32_e32 v196, s60, v167
	ds_read_b64_tr_b16 v[200:201], v196 offset:0
	ds_read_b64_tr_b16 v[202:203], v196 offset:0x800
	ds_read_b64_tr_b16 v[204:205], v196 offset:0x1000
	ds_read_b64_tr_b16 v[206:207], v196 offset:0x1800
	ds_read_b64_tr_b16 v[208:209], v196 offset:0x2000
	ds_read_b64_tr_b16 v[210:211], v196 offset:0x2800
	ds_read_b64_tr_b16 v[212:213], v196 offset:0x3000
	ds_read_b64_tr_b16 v[214:215], v196 offset:0x3800
	s_nop 0
	s_waitcnt lgkmcnt(6)
; #define SBAR() __builtin_amdgcn_sched_barrier(0)
; template <int MLA>
; __device__ __forceinline__ void partialSM(f32x16& p0, f32x16& p1, float& m_reg, float& mn, float& alpha) {
;   constexpr float SCALE = AttC<MLA>::SCALE;
;   constexpr float C = SCALE * 1.4426950408889634f;
;   float pmax = p0[0];
; #pragma unroll
;   for (int r = 1; r < 16; ++r) pmax = fmaxf(pmax, p0[r]);
; #pragma unroll
;   for (int r = 0; r < 16; ++r) pmax = fmaxf(pmax, p1[r]);
;   { auto rr = __builtin_amdgcn_permlane32_swap(__float_as_uint(pmax), __float_as_uint(pmax), false, false);
;     pmax = fmaxf(__uint_as_float(rr[0]), __uint_as_float(rr[1])); }
;   if (__builtin_expect(__all(pmax - m_reg <= THR / SCALE), 1)) { mn = m_reg; alpha = 1.f; }
;   else { mn = fmaxf(m_reg, pmax); alpha = __builtin_amdgcn_exp2f((m_reg - mn) * C); m_reg = mn; }
;   float mnC = -mn * C;
; #pragma unroll
;   for (int r = 0; r < 16; ++r) p0[r] = fmaf(p0[r], C, mnC);
; #pragma unroll
;   for (int r = 0; r < 16; ++r) p1[r] = fmaf(p1[r], C, mnC);
; #pragma unroll
;   for (int r = 0; r < 16; ++r) p0[r] = __builtin_amdgcn_exp2f(p0[r]);
; }
; template <int D0> __device__ __forceinline__ void pv_one_t(f32x16& od, int vb, bf16x8 pa0, bf16x8 pa1, bf16x8 pa2, bf16x8 pa3) {
;   const s16x4 l0 = tr_read<v_rd_off(D0, 0, 0)>(vb), h0 = tr_read<v_rd_off(D0, 0, 1)>(vb), l1 = tr_read<v_rd_off(D0, 1, 0)>(vb), h1 = tr_read<v_rd_off(D0, 1, 1)>(vb);
;   const s16x4 l2 = tr_read<v_rd_off(D0, 2, 0)>(vb), h2 = tr_read<v_rd_off(D0, 2, 1)>(vb), l3 = tr_read<v_rd_off(D0, 3, 0)>(vb), h3 = tr_read<v_rd_off(D0, 3, 1)>(vb);
;   asm volatile("s_waitcnt lgkmcnt(0)" ::: "memory"); SBAR();
;     ...
;   od = __builtin_amdgcn_mfma_f32_32x32x16_bf16(PK(l0, h0), pa0, od, 0, 0, 0);
;   od = __builtin_amdgcn_mfma_f32_32x32x16_bf16(PK(l1, h1), pa1, od, 0, 0, 0);
;   od = __builtin_amdgcn_mfma_f32_32x32x16_bf16(PK(l2, h2), pa2, od, 0, 0, 0);
;   od = __builtin_amdgcn_mfma_f32_32x32x16_bf16(PK(l3, h3), pa3, od, 0, 0, 0);
;     ...
; }
; __device__ __forceinline__ void pv_d0_t(f32x16* o, int vb, bf16x8 pa0, bf16x8 pa1, bf16x8 pa2, bf16x8 pa3) {
;   pv_one_t<0>(o[0], vb, pa0, pa1, pa2, pa3); pv_one_t<1>(o[1], vb, pa0, pa1, pa2, pa3); pv_one_t<2>(o[2], vb, pa0, pa1, pa2, pa3); pv_one_t<3>(o[3], vb, pa0, pa1, pa2, pa3);
; }
	v_mfma_f32_32x32x16_bf16 v[0:15], v[200:203], v[144:147], v[0:15]
	ds_read_b64_tr_b16 v[200:201], v196 offset:0x200
	ds_read_b64_tr_b16 v[202:203], v196 offset:0xa00
	s_waitcnt lgkmcnt(6)
	v_mfma_f32_32x32x16_bf16 v[0:15], v[204:207], v[148:151], v[0:15]
	ds_read_b64_tr_b16 v[204:205], v196 offset:0x1200
	ds_read_b64_tr_b16 v[206:207], v196 offset:0x1a00
	s_waitcnt lgkmcnt(6)
	v_mfma_f32_32x32x16_bf16 v[0:15], v[208:211], v[152:155], v[0:15]
	ds_read_b64_tr_b16 v[208:209], v196 offset:0x2200
	ds_read_b64_tr_b16 v[210:211], v196 offset:0x2a00
	s_waitcnt lgkmcnt(6)
	v_mfma_f32_32x32x16_bf16 v[0:15], v[212:215], v[170:173], v[0:15]
	ds_read_b64_tr_b16 v[212:213], v196 offset:0x3200
	ds_read_b64_tr_b16 v[214:215], v196 offset:0x3a00
	s_waitcnt lgkmcnt(6)
	v_mfma_f32_32x32x16_bf16 v[48:63], v[200:203], v[144:147], v[48:63]
	ds_read_b64_tr_b16 v[200:201], v196 offset:0x400
	ds_read_b64_tr_b16 v[202:203], v196 offset:0xc00
	s_waitcnt lgkmcnt(6)
	v_mfma_f32_32x32x16_bf16 v[48:63], v[204:207], v[148:151], v[48:63]
	ds_read_b64_tr_b16 v[204:205], v196 offset:0x1400
	ds_read_b64_tr_b16 v[206:207], v196 offset:0x1c00
	s_waitcnt lgkmcnt(6)
	v_mfma_f32_32x32x16_bf16 v[48:63], v[208:211], v[152:155], v[48:63]
	ds_read_b64_tr_b16 v[208:209], v196 offset:0x2400
	ds_read_b64_tr_b16 v[210:211], v196 offset:0x2c00
	s_waitcnt lgkmcnt(6)
	v_mfma_f32_32x32x16_bf16 v[48:63], v[212:215], v[170:173], v[48:63]
	ds_read_b64_tr_b16 v[212:213], v196 offset:0x3400
	ds_read_b64_tr_b16 v[214:215], v196 offset:0x3c00
	s_waitcnt lgkmcnt(6)
	v_mfma_f32_32x32x16_bf16 v[32:47], v[200:203], v[144:147], v[32:47]
	ds_read_b64_tr_b16 v[200:201], v196 offset:0x600
	ds_read_b64_tr_b16 v[202:203], v196 offset:0xe00
	s_waitcnt lgkmcnt(6)
	v_mfma_f32_32x32x16_bf16 v[32:47], v[204:207], v[148:151], v[32:47]
	ds_read_b64_tr_b16 v[204:205], v196 offset:0x1600
	ds_read_b64_tr_b16 v[206:207], v196 offset:0x1e00
	s_waitcnt lgkmcnt(6)
	v_mfma_f32_32x32x16_bf16 v[32:47], v[208:211], v[152:155], v[32:47]
	ds_read_b64_tr_b16 v[208:209], v196 offset:0x2600
	ds_read_b64_tr_b16 v[210:211], v196 offset:0x2e00
	s_waitcnt lgkmcnt(6)
	v_mfma_f32_32x32x16_bf16 v[32:47], v[212:215], v[170:173], v[32:47]
	ds_read_b64_tr_b16 v[212:213], v196 offset:0x3600
	ds_read_b64_tr_b16 v[214:215], v196 offset:0x3e00
	s_waitcnt lgkmcnt(6)
	v_mfma_f32_32x32x16_bf16 v[16:31], v[200:203], v[144:147], v[16:31]
	v_max_f32_e32 v144, v80, v81
	v_max3_f32 v144, v144, v82, v83
	v_max3_f32 v144, v144, v84, v85
	v_max3_f32 v144, v144, v86, v87
	v_max3_f32 v144, v144, v88, v89
	v_max3_f32 v144, v144, v90, v91
	v_max3_f32 v144, v144, v92, v93
	s_waitcnt lgkmcnt(4)
	v_mfma_f32_32x32x16_bf16 v[16:31], v[204:207], v[148:151], v[16:31]
	v_max3_f32 v144, v144, v94, v95
	v_max3_f32 v144, v144, v64, v65
	v_max3_f32 v144, v144, v66, v67
	v_max3_f32 v144, v144, v68, v69
	v_max3_f32 v144, v144, v70, v71
	v_max3_f32 v144, v144, v72, v73
	v_max3_f32 v144, v144, v74, v75
	v_max3_f32 v144, v144, v76, v77
	s_waitcnt lgkmcnt(2)
	v_mfma_f32_32x32x16_bf16 v[16:31], v[208:211], v[152:155], v[16:31]
	v_max3_f32 v144, v144, v78, v79
	v_mov_b32_e32 v145, v144
	s_nop 1
	v_permlane32_swap_b32_e32 v144, v145
	v_max_f32_e32 v144, v144, v145
	v_cmp_ge_f32_e32 vcc, s63, v144
	s_waitcnt lgkmcnt(0)
	v_mfma_f32_32x32x16_bf16 v[16:31], v[212:215], v[170:173], v[16:31]
	s_cmp_eq_u64 vcc, exec
	s_waitcnt vmcnt(0) lgkmcnt(0)
	s_barrier
	s_cbranch_scc1 .Lal_c_m1
	v_max_f32_e32 v242, 0, v144
	v_exp_f32_e64 v152, -v242
	s_nop 0
	v_pk_mul_f32 v[14:15], v[14:15], v[152:153] op_sel_hi:[1,0]
	v_pk_mul_f32 v[12:13], v[12:13], v[152:153] op_sel_hi:[1,0]
	v_pk_mul_f32 v[10:11], v[10:11], v[152:153] op_sel_hi:[1,0]
	v_pk_mul_f32 v[8:9], v[8:9], v[152:153] op_sel_hi:[1,0]
	v_pk_mul_f32 v[6:7], v[6:7], v[152:153] op_sel_hi:[1,0]
	v_pk_mul_f32 v[4:5], v[4:5], v[152:153] op_sel_hi:[1,0]
	v_pk_mul_f32 v[2:3], v[2:3], v[152:153] op_sel_hi:[1,0]
	v_pk_mul_f32 v[0:1], v[0:1], v[152:153] op_sel_hi:[1,0]
	v_pk_mul_f32 v[62:63], v[62:63], v[152:153] op_sel_hi:[1,0]
	v_pk_mul_f32 v[60:61], v[60:61], v[152:153] op_sel_hi:[1,0]
	v_pk_mul_f32 v[58:59], v[58:59], v[152:153] op_sel_hi:[1,0]
	v_pk_mul_f32 v[56:57], v[56:57], v[152:153] op_sel_hi:[1,0]
	v_pk_mul_f32 v[54:55], v[54:55], v[152:153] op_sel_hi:[1,0]
	v_pk_mul_f32 v[52:53], v[52:53], v[152:153] op_sel_hi:[1,0]
	v_pk_mul_f32 v[50:51], v[50:51], v[152:153] op_sel_hi:[1,0]
	v_pk_mul_f32 v[48:49], v[48:49], v[152:153] op_sel_hi:[1,0]
	v_pk_mul_f32 v[46:47], v[46:47], v[152:153] op_sel_hi:[1,0]
	v_pk_mul_f32 v[44:45], v[44:45], v[152:153] op_sel_hi:[1,0]
	v_pk_mul_f32 v[42:43], v[42:43], v[152:153] op_sel_hi:[1,0]
	v_pk_mul_f32 v[40:41], v[40:41], v[152:153] op_sel_hi:[1,0]
	v_pk_mul_f32 v[38:39], v[38:39], v[152:153] op_sel_hi:[1,0]
	v_pk_mul_f32 v[36:37], v[36:37], v[152:153] op_sel_hi:[1,0]
	v_pk_mul_f32 v[34:35], v[34:35], v[152:153] op_sel_hi:[1,0]
	v_pk_mul_f32 v[32:33], v[32:33], v[152:153] op_sel_hi:[1,0]
	v_pk_mul_f32 v[30:31], v[30:31], v[152:153] op_sel_hi:[1,0]
	v_pk_mul_f32 v[28:29], v[28:29], v[152:153] op_sel_hi:[1,0]
	v_pk_mul_f32 v[26:27], v[26:27], v[152:153] op_sel_hi:[1,0]
	v_pk_mul_f32 v[24:25], v[24:25], v[152:153] op_sel_hi:[1,0]
	v_pk_mul_f32 v[22:23], v[22:23], v[152:153] op_sel_hi:[1,0]
	v_pk_mul_f32 v[20:21], v[20:21], v[152:153] op_sel_hi:[1,0]
	v_pk_mul_f32 v[18:19], v[18:19], v[152:153] op_sel_hi:[1,0]
	v_pk_mul_f32 v[16:17], v[16:17], v[152:153] op_sel_hi:[1,0]
	v_sub_f32_e32 v80, v80, v242
	v_sub_f32_e32 v81, v81, v242
	v_sub_f32_e32 v82, v82, v242
	v_sub_f32_e32 v83, v83, v242
	v_sub_f32_e32 v84, v84, v242
	v_sub_f32_e32 v85, v85, v242
	v_sub_f32_e32 v86, v86, v242
	v_sub_f32_e32 v87, v87, v242
	v_sub_f32_e32 v88, v88, v242
	v_sub_f32_e32 v89, v89, v242
	v_sub_f32_e32 v90, v90, v242
	v_sub_f32_e32 v91, v91, v242
	v_sub_f32_e32 v92, v92, v242
	v_sub_f32_e32 v93, v93, v242
	v_sub_f32_e32 v94, v94, v242
	v_sub_f32_e32 v95, v95, v242
	v_sub_f32_e32 v64, v64, v242
	v_sub_f32_e32 v65, v65, v242
	v_sub_f32_e32 v66, v66, v242
	v_sub_f32_e32 v67, v67, v242
	v_sub_f32_e32 v68, v68, v242
	v_sub_f32_e32 v69, v69, v242
	v_sub_f32_e32 v70, v70, v242
	v_sub_f32_e32 v71, v71, v242
	v_sub_f32_e32 v72, v72, v242
	v_sub_f32_e32 v73, v73, v242
	v_sub_f32_e32 v74, v74, v242
	v_sub_f32_e32 v75, v75, v242
	v_sub_f32_e32 v76, v76, v242
	v_sub_f32_e32 v77, v77, v242
	v_sub_f32_e32 v78, v78, v242
	v_sub_f32_e32 v79, v79, v242
	v_sub_f32_e32 v226, v226, v242
	v_sub_f32_e32 v227, v227, v242
	v_sub_f32_e32 v228, v228, v242
	v_sub_f32_e32 v229, v229, v242
	v_sub_f32_e32 v230, v230, v242
	v_sub_f32_e32 v231, v231, v242
	v_sub_f32_e32 v232, v232, v242
	v_sub_f32_e32 v233, v233, v242
	v_sub_f32_e32 v234, v234, v242
	v_sub_f32_e32 v235, v235, v242
	v_sub_f32_e32 v236, v236, v242
	v_sub_f32_e32 v237, v237, v242
	v_sub_f32_e32 v238, v238, v242
	v_sub_f32_e32 v239, v239, v242
	v_sub_f32_e32 v240, v240, v242
	v_sub_f32_e32 v241, v241, v242
	s_branch .LBB0_117

; __device__ __forceinline__ void finishSM(f32x16& p0, f32x16& p1, float alpha, float& l_reg, bf16x8& pa0, bf16x8& pa1, bf16x8& pa2, bf16x8& pa3) {
; #pragma unroll
;   for (int r = 0; r < 16; ++r) p1[r] = __builtin_amdgcn_exp2f(p1[r]);
;   float ps = 0;
; #pragma unroll
;   for (int r = 0; r < 16; ++r) ps += p0[r];
; #pragma unroll
;   for (int r = 0; r < 16; ++r) ps += p1[r];
;   { auto rr = __builtin_amdgcn_permlane32_swap(__float_as_uint(ps), __float_as_uint(ps), false, false);
;     ps = __uint_as_float(rr[0]) + __uint_as_float(rr[1]); }
;   l_reg = l_reg * alpha + ps;
;     ...
;   PK4(p0, 0, pa0); PK4(p0, 8, pa1); PK4(p1, 0, pa2); PK4(p1, 8, pa3);
;     ...
; }
; template <int BUFOFF>
; __device__ __forceinline__ void qkt_mla(f32x16& p0, f32x16& p1, const int* ka, const bf16x8* qr, const char* qlds) {
;   typedef __attribute__((address_space(3))) const bf16x8* lp;
;   p0 = f32x16{}; p1 = f32x16{};
; #pragma unroll
;   for (int d0 = 0; d0 < 12; ++d0) {
;     const int a = ka[d0 & 3] + (d0 >> 2) * 128 + BUFOFF;
;     const bf16x8 b0 = *(lp)(a), b1 = *(lp)(a + 12288);
;     bf16x8 qf;
;     qf = qr[d0];
;     p0 = __builtin_amdgcn_mfma_f32_32x32x16_bf16(b0, qf, p0, 0, 0, 0);
;     p1 = __builtin_amdgcn_mfma_f32_32x32x16_bf16(b1, qf, p1, 0, 0, 0);
;   }
; }
.LBB0_117:
	v_exp_f32_e32 v155, v64
	v_exp_f32_e32 v170, v65
	v_exp_f32_e32 v171, v66
	v_exp_f32_e32 v172, v67
	v_exp_f32_e32 v173, v68
	v_exp_f32_e32 v197, v69
	v_exp_f32_e32 v199, v70
	v_exp_f32_e32 v200, v71
	v_exp_f32_e32 v201, v72
	v_exp_f32_e32 v202, v73
	v_exp_f32_e32 v203, v74
	v_exp_f32_e32 v204, v75
	v_exp_f32_e32 v205, v76
	v_exp_f32_e32 v222, v77
	v_exp_f32_e32 v223, v78
	v_exp_f32_e32 v154, v79
	v_exp_f32_e32 v206, v80
	v_exp_f32_e32 v207, v81
	v_exp_f32_e32 v208, v82
	v_exp_f32_e32 v209, v83
	v_exp_f32_e32 v210, v84
	v_exp_f32_e32 v211, v85
	v_exp_f32_e32 v212, v86
	v_exp_f32_e32 v213, v87
	v_exp_f32_e32 v214, v88
	v_exp_f32_e32 v215, v89
	v_exp_f32_e32 v216, v90
	v_exp_f32_e32 v217, v91
	v_exp_f32_e32 v218, v92
	v_exp_f32_e32 v219, v93
	v_exp_f32_e32 v220, v94
	v_exp_f32_e32 v221, v95
	ds_read_b128 v[64:67], v169
	ds_read_b128 v[68:71], v169 offset:12288
	ds_read_b128 v[144:147], v190
	ds_read_b128 v[148:151], v190 offset:12288
	v_mov_b32_e32 v224, v155
	s_waitcnt lgkmcnt(0)
	v_mfma_f32_32x32x16_bf16 v[80:95], v[64:67], v[140:143], v[226:241]
	v_mfma_f32_32x32x16_bf16 v[64:79], v[68:71], v[140:143], v[226:241]
	v_mov_b32_e32 v225, v154
	v_mfma_f32_32x32x16_bf16 v[80:95], v[144:147], v[136:139], v[80:95]
	v_mfma_f32_32x32x16_bf16 v[64:79], v[148:151], v[136:139], v[64:79]
	ds_read_b128 v[144:147], v193
	ds_read_b128 v[148:151], v193 offset:12288
	s_waitcnt lgkmcnt(0)
	v_mfma_f32_32x32x16_bf16 v[80:95], v[144:147], v[132:135], v[80:95]
	v_mfma_f32_32x32x16_bf16 v[64:79], v[148:151], v[132:135], v[64:79]
	ds_read_b128 v[144:147], v192
	ds_read_b128 v[148:151], v192 offset:12288
	s_waitcnt lgkmcnt(0)
	v_mfma_f32_32x32x16_bf16 v[80:95], v[144:147], v[128:131], v[80:95]
	v_mfma_f32_32x32x16_bf16 v[64:79], v[148:151], v[128:131], v[64:79]
	ds_read_b128 v[144:147], v169 offset:128
	ds_read_b128 v[148:151], v169 offset:12416
	s_waitcnt lgkmcnt(0)
	v_mfma_f32_32x32x16_bf16 v[80:95], v[144:147], v[124:127], v[80:95]
	v_mfma_f32_32x32x16_bf16 v[64:79], v[148:151], v[124:127], v[64:79]
	ds_read_b128 v[144:147], v190 offset:128
	ds_read_b128 v[148:151], v190 offset:12416
	s_waitcnt lgkmcnt(0)
	v_mfma_f32_32x32x16_bf16 v[80:95], v[144:147], v[120:123], v[80:95]
	v_mfma_f32_32x32x16_bf16 v[64:79], v[148:151], v[120:123], v[64:79]
	ds_read_b128 v[144:147], v193 offset:128
	ds_read_b128 v[148:151], v193 offset:12416
	s_waitcnt lgkmcnt(0)
	v_mfma_f32_32x32x16_bf16 v[80:95], v[144:147], v[116:119], v[80:95]
	v_mfma_f32_32x32x16_bf16 v[64:79], v[148:151], v[116:119], v[64:79]
	ds_read_b128 v[144:147], v192 offset:128
	ds_read_b128 v[148:151], v192 offset:12416
	s_waitcnt lgkmcnt(0)
	v_mfma_f32_32x32x16_bf16 v[80:95], v[144:147], v[112:115], v[80:95]
	v_mfma_f32_32x32x16_bf16 v[64:79], v[148:151], v[112:115], v[64:79]
	ds_read_b128 v[144:147], v169 offset:256
	ds_read_b128 v[148:151], v169 offset:12544
	s_waitcnt lgkmcnt(0)
	v_mfma_f32_32x32x16_bf16 v[80:95], v[144:147], v[108:111], v[80:95]
	v_mfma_f32_32x32x16_bf16 v[64:79], v[148:151], v[108:111], v[64:79]
	ds_read_b128 v[144:147], v190 offset:256
	ds_read_b128 v[148:151], v190 offset:12544
	s_waitcnt lgkmcnt(0)
	v_mfma_f32_32x32x16_bf16 v[80:95], v[144:147], v[104:107], v[80:95]
	v_mfma_f32_32x32x16_bf16 v[64:79], v[148:151], v[104:107], v[64:79]
	ds_read_b128 v[144:147], v193 offset:256
	ds_read_b128 v[148:151], v193 offset:12544
	s_waitcnt lgkmcnt(0)
	v_mfma_f32_32x32x16_bf16 v[80:95], v[144:147], v[100:103], v[80:95]
	v_mfma_f32_32x32x16_bf16 v[64:79], v[148:151], v[100:103], v[64:79]
	ds_read_b128 v[144:147], v192 offset:256
	ds_read_b128 v[148:151], v192 offset:12544
	s_waitcnt lgkmcnt(0)
	v_mfma_f32_32x32x16_bf16 v[80:95], v[144:147], v[96:99], v[80:95]
	v_add_f32_e32 v144, v214, v206
	v_add_f32_e32 v243, v215, v207
	v_add_f32_e32 v244, v216, v208
	v_add_f32_e32 v245, v217, v209
	v_add_f32_e32 v246, v218, v210
	v_add_f32_e32 v247, v219, v211
	v_add_f32_e32 v251, v220, v212
	v_add_f32_e32 v252, v221, v213
	v_add_f32_e32 v144, v224, v144
	v_add_f32_e32 v243, v170, v243
	v_add_f32_e32 v244, v171, v244
	v_add_f32_e32 v245, v172, v245
	v_add_f32_e32 v246, v173, v246
	v_add_f32_e32 v247, v197, v247
	v_add_f32_e32 v251, v199, v251
	v_add_f32_e32 v252, v200, v252
	v_add_f32_e32 v144, v201, v144
	v_add_f32_e32 v243, v202, v243
	v_mfma_f32_32x32x16_bf16 v[64:79], v[148:151], v[96:99], v[64:79]
	v_add_f32_e32 v244, v203, v244
	v_add_f32_e32 v245, v204, v245
	v_add_f32_e32 v246, v205, v246
	v_add_f32_e32 v247, v222, v247
	v_add_f32_e32 v251, v223, v251
	v_add_f32_e32 v252, v225, v252
	v_add_f32_e32 v144, v144, v243
	v_add_f32_e32 v244, v244, v245
	v_add_f32_e32 v246, v246, v247
	v_add_f32_e32 v251, v251, v252
	v_add_f32_e32 v144, v144, v244
	v_add_f32_e32 v246, v246, v251
	v_add_f32_e32 v154, v144, v246
	v_mov_b32_e32 v155, v154
	v_cvt_pk_bf16_f32 v144, v206, v207
	v_cvt_pk_bf16_f32 v145, v208, v209
	v_cvt_pk_bf16_f32 v146, v210, v211
	v_cvt_pk_bf16_f32 v147, v212, v213
	s_nop 1
	v_permlane32_swap_b32_e32 v154, v155
	v_cvt_pk_bf16_f32 v148, v214, v215
	v_cvt_pk_bf16_f32 v149, v216, v217
	v_cvt_pk_bf16_f32 v150, v218, v219
	v_cvt_pk_bf16_f32 v151, v220, v221
	v_cvt_pk_bf16_f32 v170, v224, v170
	v_cvt_pk_bf16_f32 v171, v171, v172
	v_cvt_pk_bf16_f32 v172, v173, v197
	v_cvt_pk_bf16_f32 v173, v199, v200
	v_cvt_pk_bf16_f32 v200, v201, v202
	v_cvt_pk_bf16_f32 v201, v203, v204
	v_cvt_pk_bf16_f32 v202, v205, v222
	v_cvt_pk_bf16_f32 v203, v223, v225
	s_nop 0
	s_add_u32 s4, s56, 0x17090000
	s_addc_u32 s5, s57, 0
	s_add_u32 s56, s58, 0x1a060000
	s_mov_b32 m0, s16
	s_addc_u32 s57, s59, 0
	s_add_i32 s58, s40, s60
	global_load_lds_dwordx4 v188, s[4:5]
	s_mov_b32 m0, s17
	s_nop 0
	global_load_lds_dwordx4 v189, s[4:5]
	s_mov_b32 m0, s44
	s_nop 0
	global_load_lds_dwordx4 v191, s[4:5]
	s_mov_b32 m0, s58
	s_nop 0
	global_load_lds_dwordx4 v194, s[56:57]
	s_add_i32 m0, s58, 0x2000
	s_nop 0
	global_load_lds_dwordx4 v195, s[56:57]
	v_lshl_add_u32 v197, s55, 14, v167
	ds_read_b64_tr_b16 v[204:205], v197 offset:0
	ds_read_b64_tr_b16 v[206:207], v197 offset:0x800
	ds_read_b64_tr_b16 v[208:209], v197 offset:0x1000
	ds_read_b64_tr_b16 v[210:211], v197 offset:0x1800
	ds_read_b64_tr_b16 v[212:213], v197 offset:0x2000
	ds_read_b64_tr_b16 v[214:215], v197 offset:0x2800
	ds_read_b64_tr_b16 v[216:217], v197 offset:0x3000
	ds_read_b64_tr_b16 v[218:219], v197 offset:0x3800
	s_nop 0
	s_waitcnt lgkmcnt(6)
; #define SBAR() __builtin_amdgcn_sched_barrier(0)
; template <int MLA>
; __device__ __forceinline__ void partialSM(f32x16& p0, f32x16& p1, float& m_reg, float& mn, float& alpha) {
;   constexpr float SCALE = AttC<MLA>::SCALE;
;   constexpr float C = SCALE * 1.4426950408889634f;
;   float pmax = p0[0];
; #pragma unroll
;   for (int r = 1; r < 16; ++r) pmax = fmaxf(pmax, p0[r]);
; #pragma unroll
;   for (int r = 0; r < 16; ++r) pmax = fmaxf(pmax, p1[r]);
;   { auto rr = __builtin_amdgcn_permlane32_swap(__float_as_uint(pmax), __float_as_uint(pmax), false, false);
;     pmax = fmaxf(__uint_as_float(rr[0]), __uint_as_float(rr[1])); }
;   if (__builtin_expect(__all(pmax - m_reg <= THR / SCALE), 1)) { mn = m_reg; alpha = 1.f; }
;   else { mn = fmaxf(m_reg, pmax); alpha = __builtin_amdgcn_exp2f((m_reg - mn) * C); m_reg = mn; }
;   float mnC = -mn * C;
; #pragma unroll
;   for (int r = 0; r < 16; ++r) p0[r] = fmaf(p0[r], C, mnC);
; #pragma unroll
;   for (int r = 0; r < 16; ++r) p1[r] = fmaf(p1[r], C, mnC);
; #pragma unroll
;   for (int r = 0; r < 16; ++r) p0[r] = __builtin_amdgcn_exp2f(p0[r]);
; }
; template <int D0> __device__ __forceinline__ void pv_one_t(f32x16& od, int vb, bf16x8 pa0, bf16x8 pa1, bf16x8 pa2, bf16x8 pa3) {
;   const s16x4 l0 = tr_read<v_rd_off(D0, 0, 0)>(vb), h0 = tr_read<v_rd_off(D0, 0, 1)>(vb), l1 = tr_read<v_rd_off(D0, 1, 0)>(vb), h1 = tr_read<v_rd_off(D0, 1, 1)>(vb);
;   const s16x4 l2 = tr_read<v_rd_off(D0, 2, 0)>(vb), h2 = tr_read<v_rd_off(D0, 2, 1)>(vb), l3 = tr_read<v_rd_off(D0, 3, 0)>(vb), h3 = tr_read<v_rd_off(D0, 3, 1)>(vb);
;   asm volatile("s_waitcnt lgkmcnt(0)" ::: "memory"); SBAR();
;     ...
;   od = __builtin_amdgcn_mfma_f32_32x32x16_bf16(PK(l0, h0), pa0, od, 0, 0, 0);
;   od = __builtin_amdgcn_mfma_f32_32x32x16_bf16(PK(l1, h1), pa1, od, 0, 0, 0);
;   od = __builtin_amdgcn_mfma_f32_32x32x16_bf16(PK(l2, h2), pa2, od, 0, 0, 0);
;   od = __builtin_amdgcn_mfma_f32_32x32x16_bf16(PK(l3, h3), pa3, od, 0, 0, 0);
;     ...
; }
; __device__ __forceinline__ void pv_d0_t(f32x16* o, int vb, bf16x8 pa0, bf16x8 pa1, bf16x8 pa2, bf16x8 pa3) {
;   pv_one_t<0>(o[0], vb, pa0, pa1, pa2, pa3); pv_one_t<1>(o[1], vb, pa0, pa1, pa2, pa3); pv_one_t<2>(o[2], vb, pa0, pa1, pa2, pa3); pv_one_t<3>(o[3], vb, pa0, pa1, pa2, pa3);
; }
	v_mfma_f32_32x32x16_bf16 v[0:15], v[204:207], v[144:147], v[0:15]
	ds_read_b64_tr_b16 v[204:205], v197 offset:0x200
	ds_read_b64_tr_b16 v[206:207], v197 offset:0xa00
	s_waitcnt lgkmcnt(6)
	v_mfma_f32_32x32x16_bf16 v[0:15], v[208:211], v[148:151], v[0:15]
	ds_read_b64_tr_b16 v[208:209], v197 offset:0x1200
	ds_read_b64_tr_b16 v[210:211], v197 offset:0x1a00
	s_waitcnt lgkmcnt(6)
	v_mfma_f32_32x32x16_bf16 v[0:15], v[212:215], v[170:173], v[0:15]
	ds_read_b64_tr_b16 v[212:213], v197 offset:0x2200
	ds_read_b64_tr_b16 v[214:215], v197 offset:0x2a00
	s_waitcnt lgkmcnt(6)
	v_mfma_f32_32x32x16_bf16 v[0:15], v[216:219], v[200:203], v[0:15]
	ds_read_b64_tr_b16 v[216:217], v197 offset:0x3200
	ds_read_b64_tr_b16 v[218:219], v197 offset:0x3a00
	s_waitcnt lgkmcnt(6)
	v_mfma_f32_32x32x16_bf16 v[48:63], v[204:207], v[144:147], v[48:63]
	ds_read_b64_tr_b16 v[204:205], v197 offset:0x400
	ds_read_b64_tr_b16 v[206:207], v197 offset:0xc00
	s_waitcnt lgkmcnt(6)
	v_mfma_f32_32x32x16_bf16 v[48:63], v[208:211], v[148:151], v[48:63]
	ds_read_b64_tr_b16 v[208:209], v197 offset:0x1400
	ds_read_b64_tr_b16 v[210:211], v197 offset:0x1c00
	s_waitcnt lgkmcnt(6)
	v_mfma_f32_32x32x16_bf16 v[48:63], v[212:215], v[170:173], v[48:63]
	ds_read_b64_tr_b16 v[212:213], v197 offset:0x2400
	ds_read_b64_tr_b16 v[214:215], v197 offset:0x2c00
	s_waitcnt lgkmcnt(6)
	v_mfma_f32_32x32x16_bf16 v[48:63], v[216:219], v[200:203], v[48:63]
	ds_read_b64_tr_b16 v[216:217], v197 offset:0x3400
	ds_read_b64_tr_b16 v[218:219], v197 offset:0x3c00
	s_waitcnt lgkmcnt(6)
	v_mfma_f32_32x32x16_bf16 v[32:47], v[204:207], v[144:147], v[32:47]
	ds_read_b64_tr_b16 v[204:205], v197 offset:0x600
	ds_read_b64_tr_b16 v[206:207], v197 offset:0xe00
	s_waitcnt lgkmcnt(6)
	v_mfma_f32_32x32x16_bf16 v[32:47], v[208:211], v[148:151], v[32:47]
	ds_read_b64_tr_b16 v[208:209], v197 offset:0x1600
	ds_read_b64_tr_b16 v[210:211], v197 offset:0x1e00
	s_waitcnt lgkmcnt(6)
	v_mfma_f32_32x32x16_bf16 v[32:47], v[212:215], v[170:173], v[32:47]
	ds_read_b64_tr_b16 v[212:213], v197 offset:0x2600
	ds_read_b64_tr_b16 v[214:215], v197 offset:0x2e00
	s_waitcnt lgkmcnt(6)
	v_mfma_f32_32x32x16_bf16 v[32:47], v[216:219], v[200:203], v[32:47]
	ds_read_b64_tr_b16 v[216:217], v197 offset:0x3600
	ds_read_b64_tr_b16 v[218:219], v197 offset:0x3e00
	s_waitcnt lgkmcnt(6)
	v_mfma_f32_32x32x16_bf16 v[16:31], v[204:207], v[144:147], v[16:31]
	v_max_f32_e32 v144, v80, v81
	v_max3_f32 v144, v144, v82, v83
	v_max3_f32 v144, v144, v84, v85
	v_max3_f32 v144, v144, v86, v87
	v_max3_f32 v144, v144, v88, v89
	v_max3_f32 v144, v144, v90, v91
	v_max3_f32 v144, v144, v92, v93
	s_waitcnt lgkmcnt(4)
	v_mfma_f32_32x32x16_bf16 v[16:31], v[208:211], v[148:151], v[16:31]
	v_max3_f32 v144, v144, v94, v95
	v_max3_f32 v144, v144, v64, v65
	v_max3_f32 v144, v144, v66, v67
	v_max3_f32 v144, v144, v68, v69
	v_max3_f32 v144, v144, v70, v71
	v_max3_f32 v144, v144, v72, v73
	v_max3_f32 v144, v144, v74, v75
	v_max3_f32 v144, v144, v76, v77
	s_waitcnt lgkmcnt(2)
	v_mfma_f32_32x32x16_bf16 v[16:31], v[212:215], v[170:173], v[16:31]
	v_max3_f32 v144, v144, v78, v79
	v_mov_b32_e32 v145, v144
	s_nop 1
	v_permlane32_swap_b32_e32 v144, v145
	v_max_f32_e32 v144, v144, v145
	v_cmp_ge_f32_e32 vcc, s63, v144
	s_waitcnt lgkmcnt(0)
	v_mfma_f32_32x32x16_bf16 v[16:31], v[216:219], v[200:203], v[16:31]
	s_cmp_eq_u64 vcc, exec
	s_waitcnt vmcnt(0) lgkmcnt(0)
	s_barrier
	s_cbranch_scc1 .Lal_c_m2
	v_max_f32_e32 v242, 0, v144
	v_exp_f32_e64 v144, -v242
	s_nop 0
	v_pk_mul_f32 v[14:15], v[14:15], v[144:145] op_sel_hi:[1,0]
	v_pk_mul_f32 v[12:13], v[12:13], v[144:145] op_sel_hi:[1,0]
	v_pk_mul_f32 v[10:11], v[10:11], v[144:145] op_sel_hi:[1,0]
	v_pk_mul_f32 v[8:9], v[8:9], v[144:145] op_sel_hi:[1,0]
	v_pk_mul_f32 v[6:7], v[6:7], v[144:145] op_sel_hi:[1,0]
	v_pk_mul_f32 v[4:5], v[4:5], v[144:145] op_sel_hi:[1,0]
	v_pk_mul_f32 v[2:3], v[2:3], v[144:145] op_sel_hi:[1,0]
	v_pk_mul_f32 v[0:1], v[0:1], v[144:145] op_sel_hi:[1,0]
	v_pk_mul_f32 v[62:63], v[62:63], v[144:145] op_sel_hi:[1,0]
	v_pk_mul_f32 v[60:61], v[60:61], v[144:145] op_sel_hi:[1,0]
	v_pk_mul_f32 v[58:59], v[58:59], v[144:145] op_sel_hi:[1,0]
	v_pk_mul_f32 v[56:57], v[56:57], v[144:145] op_sel_hi:[1,0]
	v_pk_mul_f32 v[54:55], v[54:55], v[144:145] op_sel_hi:[1,0]
	v_pk_mul_f32 v[52:53], v[52:53], v[144:145] op_sel_hi:[1,0]
	v_pk_mul_f32 v[50:51], v[50:51], v[144:145] op_sel_hi:[1,0]
	v_pk_mul_f32 v[48:49], v[48:49], v[144:145] op_sel_hi:[1,0]
	v_pk_mul_f32 v[46:47], v[46:47], v[144:145] op_sel_hi:[1,0]
	v_pk_mul_f32 v[44:45], v[44:45], v[144:145] op_sel_hi:[1,0]
	v_pk_mul_f32 v[42:43], v[42:43], v[144:145] op_sel_hi:[1,0]
	v_pk_mul_f32 v[40:41], v[40:41], v[144:145] op_sel_hi:[1,0]
	v_pk_mul_f32 v[38:39], v[38:39], v[144:145] op_sel_hi:[1,0]
	v_pk_mul_f32 v[36:37], v[36:37], v[144:145] op_sel_hi:[1,0]
	v_pk_mul_f32 v[34:35], v[34:35], v[144:145] op_sel_hi:[1,0]
	v_pk_mul_f32 v[32:33], v[32:33], v[144:145] op_sel_hi:[1,0]
	v_pk_mul_f32 v[30:31], v[30:31], v[144:145] op_sel_hi:[1,0]
	v_pk_mul_f32 v[28:29], v[28:29], v[144:145] op_sel_hi:[1,0]
	v_pk_mul_f32 v[26:27], v[26:27], v[144:145] op_sel_hi:[1,0]
	v_pk_mul_f32 v[24:25], v[24:25], v[144:145] op_sel_hi:[1,0]
	v_pk_mul_f32 v[22:23], v[22:23], v[144:145] op_sel_hi:[1,0]
	v_pk_mul_f32 v[20:21], v[20:21], v[144:145] op_sel_hi:[1,0]
	v_pk_mul_f32 v[18:19], v[18:19], v[144:145] op_sel_hi:[1,0]
	v_pk_mul_f32 v[16:17], v[16:17], v[144:145] op_sel_hi:[1,0]
	v_sub_f32_e32 v80, v80, v242
	v_sub_f32_e32 v81, v81, v242
	v_sub_f32_e32 v82, v82, v242
	v_sub_f32_e32 v83, v83, v242
	v_sub_f32_e32 v84, v84, v242
	v_sub_f32_e32 v85, v85, v242
	v_sub_f32_e32 v86, v86, v242
	v_sub_f32_e32 v87, v87, v242
	v_sub_f32_e32 v88, v88, v242
	v_sub_f32_e32 v89, v89, v242
	v_sub_f32_e32 v90, v90, v242
	v_sub_f32_e32 v91, v91, v242
	v_sub_f32_e32 v92, v92, v242
	v_sub_f32_e32 v93, v93, v242
	v_sub_f32_e32 v94, v94, v242
	v_sub_f32_e32 v95, v95, v242
	v_sub_f32_e32 v64, v64, v242
	v_sub_f32_e32 v65, v65, v242
	v_sub_f32_e32 v66, v66, v242
	v_sub_f32_e32 v67, v67, v242
	v_sub_f32_e32 v68, v68, v242
	v_sub_f32_e32 v69, v69, v242
	v_sub_f32_e32 v70, v70, v242
	v_sub_f32_e32 v71, v71, v242
	v_sub_f32_e32 v72, v72, v242
	v_sub_f32_e32 v73, v73, v242
	v_sub_f32_e32 v74, v74, v242
	v_sub_f32_e32 v75, v75, v242
	v_sub_f32_e32 v76, v76, v242
	v_sub_f32_e32 v77, v77, v242
	v_sub_f32_e32 v78, v78, v242
	v_sub_f32_e32 v79, v79, v242
	v_sub_f32_e32 v226, v226, v242
	v_sub_f32_e32 v227, v227, v242
	v_sub_f32_e32 v228, v228, v242
	v_sub_f32_e32 v229, v229, v242
	v_sub_f32_e32 v230, v230, v242
	v_sub_f32_e32 v231, v231, v242
	v_sub_f32_e32 v232, v232, v242
	v_sub_f32_e32 v233, v233, v242
	v_sub_f32_e32 v234, v234, v242
	v_sub_f32_e32 v235, v235, v242
	v_sub_f32_e32 v236, v236, v242
	v_sub_f32_e32 v237, v237, v242
	v_sub_f32_e32 v238, v238, v242
	v_sub_f32_e32 v239, v239, v242
	v_sub_f32_e32 v240, v240, v242
	v_sub_f32_e32 v241, v241, v242
	s_branch .LBB0_119

; __device__ __forceinline__ void finishSM(f32x16& p0, f32x16& p1, float alpha, float& l_reg, bf16x8& pa0, bf16x8& pa1, bf16x8& pa2, bf16x8& pa3) {
; #pragma unroll
;   for (int r = 0; r < 16; ++r) p1[r] = __builtin_amdgcn_exp2f(p1[r]);
;   float ps = 0;
; #pragma unroll
;   for (int r = 0; r < 16; ++r) ps += p0[r];
; #pragma unroll
;   for (int r = 0; r < 16; ++r) ps += p1[r];
;   { auto rr = __builtin_amdgcn_permlane32_swap(__float_as_uint(ps), __float_as_uint(ps), false, false);
;     ps = __uint_as_float(rr[0]) + __uint_as_float(rr[1]); }
;   l_reg = l_reg * alpha + ps;
;     ...
;   PK4(p0, 0, pa0); PK4(p0, 8, pa1); PK4(p1, 0, pa2); PK4(p1, 8, pa3);
;     ...
; }
; template <int BUFOFF>
; __device__ __forceinline__ void qkt_diff(f32x16& p0, f32x16& p1, const int* ka, const bf16x8* qr) {
;   typedef __attribute__((address_space(3))) const bf16x8* lp;
;   p0 = f32x16{}; p1 = f32x16{};
; #pragma unroll
;   for (int d0 = 0; d0 < 4; ++d0) {
;     const int a = ka[d0] + BUFOFF;
;     const bf16x8 b0 = *(lp)(a), b1 = *(lp)(a + 8192);
;     p0 = __builtin_amdgcn_mfma_f32_32x32x16_bf16(b0, qr[d0], p0, 0, 0, 0);
;     p1 = __builtin_amdgcn_mfma_f32_32x32x16_bf16(b1, qr[d0], p1, 0, 0, 0);
;   }
; }
.LBB0_129:
	s_mov_b32 s54, s47
	s_mov_b32 s47, s52
	ds_read_b128 v[64:67], v138 offset:16384
	ds_read_b128 v[68:71], v138 offset:24576
	ds_read_b128 v[170:173], v141 offset:16384
	ds_read_b128 v[188:191], v141 offset:24576
	s_waitcnt lgkmcnt(0)
	v_mfma_f32_32x32x16_bf16 v[80:95], v[64:67], v[108:111], v[226:241]
	v_add_f32_e32 v112, v144, v113
	v_mfma_f32_32x32x16_bf16 v[64:79], v[68:71], v[108:111], v[226:241]
	v_add_f32_e32 v243, v148, v155
	v_add_f32_e32 v244, v145, v152
	v_add_f32_e32 v245, v149, v156
	v_add_f32_e32 v246, v146, v153
	v_add_f32_e32 v247, v150, v158
	v_mfma_f32_32x32x16_bf16 v[80:95], v[170:173], v[104:107], v[80:95]
	v_add_f32_e32 v251, v147, v154
	v_add_f32_e32 v252, v151, v159
	v_mov_b32_e32 v132, v124
	v_add_f32_e32 v112, v128, v112
	v_mov_b32_e32 v162, v125
	v_mfma_f32_32x32x16_bf16 v[64:79], v[188:191], v[104:107], v[64:79]
	ds_read_b128 v[170:173], v140 offset:16384
	ds_read_b128 v[188:191], v140 offset:24576
	v_add_f32_e32 v243, v129, v243
	v_mov_b32_e32 v167, v120
	v_add_f32_e32 v244, v126, v244
	v_mov_b32_e32 v169, v121
	v_add_f32_e32 v245, v127, v245
	v_add_f32_e32 v246, v132, v246
	s_waitcnt lgkmcnt(0)
	v_mfma_f32_32x32x16_bf16 v[80:95], v[170:173], v[100:103], v[80:95]
	v_add_f32_e32 v247, v162, v247
	v_add_f32_e32 v251, v167, v251
	v_add_f32_e32 v252, v169, v252
	v_mfma_f32_32x32x16_bf16 v[64:79], v[188:191], v[100:103], v[64:79]
	ds_read_b128 v[170:173], v139 offset:16384
	ds_read_b128 v[188:191], v139 offset:24576
	s_waitcnt lgkmcnt(0)
	v_mfma_f32_32x32x16_bf16 v[80:95], v[170:173], v[96:99], v[80:95]
	v_mov_b32_e32 v170, v118
	v_mov_b32_e32 v171, v117
	v_mov_b32_e32 v172, v114
	v_mov_b32_e32 v173, v115
	v_add_f32_e32 v112, v170, v112
	v_add_f32_e32 v243, v119, v243
	v_add_f32_e32 v244, v116, v244
	v_mfma_f32_32x32x16_bf16 v[64:79], v[188:191], v[96:99], v[64:79]
	v_mov_b32_e32 v188, v122
	v_mov_b32_e32 v189, v123
	v_add_f32_e32 v245, v171, v245
	v_add_f32_e32 v246, v172, v246
	v_add_f32_e32 v247, v173, v247
	v_add_f32_e32 v251, v188, v251
	v_add_f32_e32 v252, v189, v252
	v_add_f32_e32 v112, v112, v243
	v_add_f32_e32 v244, v244, v245
	v_add_f32_e32 v246, v246, v247
	v_add_f32_e32 v251, v251, v252
	v_add_f32_e32 v112, v112, v244
	v_add_f32_e32 v246, v246, v251
	v_add_f32_e32 v117, v112, v246
	v_mov_b32_e32 v118, v117
	v_cvt_pk_bf16_f32 v112, v113, v155
	v_cvt_pk_bf16_f32 v113, v152, v156
	v_cvt_pk_bf16_f32 v114, v153, v158
	s_nop 1
	v_permlane32_swap_b32_e32 v117, v118
	v_cvt_pk_bf16_f32 v115, v154, v159
	v_cvt_pk_bf16_f32 v120, v144, v148
	v_cvt_pk_bf16_f32 v121, v145, v149
	v_cvt_pk_bf16_f32 v122, v146, v150
	v_cvt_pk_bf16_f32 v123, v147, v151
	v_cvt_pk_bf16_f32 v124, v128, v129
	v_cvt_pk_bf16_f32 v125, v126, v127
	v_cvt_pk_bf16_f32 v126, v132, v162
	v_cvt_pk_bf16_f32 v127, v167, v169
	v_cvt_pk_bf16_f32 v144, v170, v119
	v_cvt_pk_bf16_f32 v145, v116, v171
	v_cvt_pk_bf16_f32 v146, v172, v173
	v_cvt_pk_bf16_f32 v147, v188, v189
	s_add_u32 s4, s14, 0x2000000
	s_mov_b32 m0, s43
	s_addc_u32 s5, s15, 0
	s_mov_b64 s[56:57], s[14:15]
	s_lshl_b32 s52, s53, 14
	s_add_i32 s55, s42, s52
	s_nop 0
	global_load_lds_dwordx4 v134, s[56:57]
	s_mov_b32 m0, s44
	s_nop 0
	global_load_lds_dwordx4 v135, s[56:57]
	s_mov_b32 m0, s55
	s_nop 0
	global_load_lds_dwordx4 v136, s[4:5]
	s_add_i32 m0, s55, 0x2000
	s_nop 0
	global_load_lds_dwordx4 v137, s[4:5]
	s_lshl_b32 s55, s47, 14
	v_add_u32_e32 v132, s55, v133
	ds_read_b64_tr_b16 v[148:149], v132 offset:0
	ds_read_b64_tr_b16 v[150:151], v132 offset:0x800
	ds_read_b64_tr_b16 v[152:153], v132 offset:0x1000
	ds_read_b64_tr_b16 v[154:155], v132 offset:0x1800
	ds_read_b64_tr_b16 v[170:171], v132 offset:0x2000
	ds_read_b64_tr_b16 v[172:173], v132 offset:0x2800
	ds_read_b64_tr_b16 v[188:189], v132 offset:0x3000
	ds_read_b64_tr_b16 v[190:191], v132 offset:0x3800
	s_nop 0
	s_waitcnt lgkmcnt(6)
	v_mfma_f32_32x32x16_bf16 v[32:47], v[148:151], v[112:115], v[32:47]
	ds_read_b64_tr_b16 v[148:149], v132 offset:0x200
	ds_read_b64_tr_b16 v[150:151], v132 offset:0xa00
	s_waitcnt lgkmcnt(6)
	v_mfma_f32_32x32x16_bf16 v[32:47], v[152:155], v[120:123], v[32:47]
	ds_read_b64_tr_b16 v[152:153], v132 offset:0x1200
	ds_read_b64_tr_b16 v[154:155], v132 offset:0x1a00
	s_waitcnt lgkmcnt(6)
	v_mfma_f32_32x32x16_bf16 v[32:47], v[170:173], v[124:127], v[32:47]
	ds_read_b64_tr_b16 v[170:171], v132 offset:0x2200
	ds_read_b64_tr_b16 v[172:173], v132 offset:0x2a00
	s_waitcnt lgkmcnt(6)
	v_mfma_f32_32x32x16_bf16 v[32:47], v[188:191], v[144:147], v[32:47]
	ds_read_b64_tr_b16 v[188:189], v132 offset:0x3200
	ds_read_b64_tr_b16 v[190:191], v132 offset:0x3a00
	s_waitcnt lgkmcnt(6)
	v_mfma_f32_32x32x16_bf16 v[48:63], v[148:151], v[112:115], v[48:63]
	ds_read_b64_tr_b16 v[148:149], v132 offset:0x400
	ds_read_b64_tr_b16 v[150:151], v132 offset:0xc00
	s_waitcnt lgkmcnt(6)
	v_mfma_f32_32x32x16_bf16 v[48:63], v[152:155], v[120:123], v[48:63]
	ds_read_b64_tr_b16 v[152:153], v132 offset:0x1400
	ds_read_b64_tr_b16 v[154:155], v132 offset:0x1c00
	s_waitcnt lgkmcnt(6)
	v_mfma_f32_32x32x16_bf16 v[48:63], v[170:173], v[124:127], v[48:63]
	ds_read_b64_tr_b16 v[170:171], v132 offset:0x2400
	ds_read_b64_tr_b16 v[172:173], v132 offset:0x2c00
	s_waitcnt lgkmcnt(6)
	v_mfma_f32_32x32x16_bf16 v[48:63], v[188:191], v[144:147], v[48:63]
	ds_read_b64_tr_b16 v[188:189], v132 offset:0x3400
	ds_read_b64_tr_b16 v[190:191], v132 offset:0x3c00
	s_waitcnt lgkmcnt(6)
; template <int MLA>
; __device__ __forceinline__ void partialSM(f32x16& p0, f32x16& p1, float& m_reg, float& mn, float& alpha) {
;     ...
;   float pmax = p0[0];
; #pragma unroll
;   for (int r = 1; r < 16; ++r) pmax = fmaxf(pmax, p0[r]);
; #pragma unroll
;   for (int r = 0; r < 16; ++r) pmax = fmaxf(pmax, p1[r]);
;   { auto rr = __builtin_amdgcn_permlane32_swap(__float_as_uint(pmax), __float_as_uint(pmax), false, false);
;     pmax = fmaxf(__uint_as_float(rr[0]), __uint_as_float(rr[1])); }
;   if (__builtin_expect(__all(pmax - m_reg <= THR / SCALE), 1)) { mn = m_reg; alpha = 1.f; }
;   else { mn = fmaxf(m_reg, pmax); alpha = __builtin_amdgcn_exp2f((m_reg - mn) * C); m_reg = mn; }
;   float mnC = -mn * C;
; #pragma unroll
;   for (int r = 0; r < 16; ++r) p0[r] = fmaf(p0[r], C, mnC);
; #pragma unroll
;   for (int r = 0; r < 16; ++r) p1[r] = fmaf(p1[r], C, mnC);
; #pragma unroll
;   for (int r = 0; r < 16; ++r) p0[r] = __builtin_amdgcn_exp2f(p0[r]);
; }
	v_mfma_f32_32x32x16_bf16 v[16:31], v[148:151], v[112:115], v[16:31]
	ds_read_b64_tr_b16 v[148:149], v132 offset:0x600
	ds_read_b64_tr_b16 v[150:151], v132 offset:0xe00
	s_waitcnt lgkmcnt(6)
	v_mfma_f32_32x32x16_bf16 v[16:31], v[152:155], v[120:123], v[16:31]
	ds_read_b64_tr_b16 v[152:153], v132 offset:0x1600
	ds_read_b64_tr_b16 v[154:155], v132 offset:0x1e00
	s_waitcnt lgkmcnt(6)
	v_mfma_f32_32x32x16_bf16 v[16:31], v[170:173], v[124:127], v[16:31]
	ds_read_b64_tr_b16 v[170:171], v132 offset:0x2600
	ds_read_b64_tr_b16 v[172:173], v132 offset:0x2e00
	s_waitcnt lgkmcnt(6)
	v_mfma_f32_32x32x16_bf16 v[16:31], v[188:191], v[144:147], v[16:31]
	ds_read_b64_tr_b16 v[188:189], v132 offset:0x3600
	ds_read_b64_tr_b16 v[190:191], v132 offset:0x3e00
	s_waitcnt lgkmcnt(6)
	v_mfma_f32_32x32x16_bf16 v[0:15], v[148:151], v[112:115], v[0:15]
	v_max_f32_e32 v112, v80, v81
	v_max3_f32 v112, v112, v82, v83
	v_max3_f32 v112, v112, v84, v85
	v_max3_f32 v112, v112, v86, v87
	v_max3_f32 v112, v112, v88, v89
	v_max3_f32 v112, v112, v90, v91
	v_max3_f32 v112, v112, v92, v93
	s_waitcnt lgkmcnt(4)
	v_mfma_f32_32x32x16_bf16 v[0:15], v[152:155], v[120:123], v[0:15]
	v_max3_f32 v112, v112, v94, v95
	v_max3_f32 v112, v112, v64, v65
	v_max3_f32 v112, v112, v66, v67
	v_max3_f32 v112, v112, v68, v69
	v_max3_f32 v112, v112, v70, v71
	v_max3_f32 v112, v112, v72, v73
	v_max3_f32 v112, v112, v74, v75
	v_max3_f32 v112, v112, v76, v77
	s_waitcnt lgkmcnt(2)
	v_mfma_f32_32x32x16_bf16 v[0:15], v[170:173], v[124:127], v[0:15]
	v_max3_f32 v112, v112, v78, v79
	v_mov_b32_e32 v113, v112
	s_nop 1
	v_permlane32_swap_b32_e32 v112, v113
	v_max_f32_e32 v112, v112, v113
	v_cmp_ge_f32_e32 vcc, s70, v112
	s_waitcnt lgkmcnt(0)
	v_mfma_f32_32x32x16_bf16 v[0:15], v[188:191], v[144:147], v[0:15]
	s_cmp_eq_u64 vcc, exec
	s_waitcnt vmcnt(0) lgkmcnt(0)
	s_barrier
	s_cbranch_scc1 .Lal_c_d1
	v_max_f32_e32 v242, 0, v112
	v_exp_f32_e64 v116, -v242
	s_nop 0
	v_pk_mul_f32 v[46:47], v[46:47], v[116:117] op_sel_hi:[1,0]
	v_pk_mul_f32 v[44:45], v[44:45], v[116:117] op_sel_hi:[1,0]
	v_pk_mul_f32 v[42:43], v[42:43], v[116:117] op_sel_hi:[1,0]
	v_pk_mul_f32 v[40:41], v[40:41], v[116:117] op_sel_hi:[1,0]
	v_pk_mul_f32 v[38:39], v[38:39], v[116:117] op_sel_hi:[1,0]
	v_pk_mul_f32 v[36:37], v[36:37], v[116:117] op_sel_hi:[1,0]
	v_pk_mul_f32 v[34:35], v[34:35], v[116:117] op_sel_hi:[1,0]
	v_pk_mul_f32 v[32:33], v[32:33], v[116:117] op_sel_hi:[1,0]
	v_pk_mul_f32 v[62:63], v[62:63], v[116:117] op_sel_hi:[1,0]
	v_pk_mul_f32 v[60:61], v[60:61], v[116:117] op_sel_hi:[1,0]
	v_pk_mul_f32 v[58:59], v[58:59], v[116:117] op_sel_hi:[1,0]
	v_pk_mul_f32 v[56:57], v[56:57], v[116:117] op_sel_hi:[1,0]
	v_pk_mul_f32 v[54:55], v[54:55], v[116:117] op_sel_hi:[1,0]
	v_pk_mul_f32 v[52:53], v[52:53], v[116:117] op_sel_hi:[1,0]
	v_pk_mul_f32 v[50:51], v[50:51], v[116:117] op_sel_hi:[1,0]
	v_pk_mul_f32 v[48:49], v[48:49], v[116:117] op_sel_hi:[1,0]
	v_pk_mul_f32 v[30:31], v[30:31], v[116:117] op_sel_hi:[1,0]
	v_pk_mul_f32 v[28:29], v[28:29], v[116:117] op_sel_hi:[1,0]
	v_pk_mul_f32 v[26:27], v[26:27], v[116:117] op_sel_hi:[1,0]
	v_pk_mul_f32 v[24:25], v[24:25], v[116:117] op_sel_hi:[1,0]
	v_pk_mul_f32 v[22:23], v[22:23], v[116:117] op_sel_hi:[1,0]
	v_pk_mul_f32 v[20:21], v[20:21], v[116:117] op_sel_hi:[1,0]
	v_pk_mul_f32 v[18:19], v[18:19], v[116:117] op_sel_hi:[1,0]
	v_pk_mul_f32 v[16:17], v[16:17], v[116:117] op_sel_hi:[1,0]
	v_pk_mul_f32 v[14:15], v[14:15], v[116:117] op_sel_hi:[1,0]
	v_pk_mul_f32 v[12:13], v[12:13], v[116:117] op_sel_hi:[1,0]
	v_pk_mul_f32 v[10:11], v[10:11], v[116:117] op_sel_hi:[1,0]
	v_pk_mul_f32 v[8:9], v[8:9], v[116:117] op_sel_hi:[1,0]
	v_pk_mul_f32 v[6:7], v[6:7], v[116:117] op_sel_hi:[1,0]
	v_pk_mul_f32 v[4:5], v[4:5], v[116:117] op_sel_hi:[1,0]
	v_pk_mul_f32 v[2:3], v[2:3], v[116:117] op_sel_hi:[1,0]
	v_pk_mul_f32 v[0:1], v[0:1], v[116:117] op_sel_hi:[1,0]
	v_sub_f32_e32 v80, v80, v242
	v_sub_f32_e32 v81, v81, v242
	v_sub_f32_e32 v82, v82, v242
	v_sub_f32_e32 v83, v83, v242
	v_sub_f32_e32 v84, v84, v242
	v_sub_f32_e32 v85, v85, v242
	v_sub_f32_e32 v86, v86, v242
	v_sub_f32_e32 v87, v87, v242
	v_sub_f32_e32 v88, v88, v242
	v_sub_f32_e32 v89, v89, v242
	v_sub_f32_e32 v90, v90, v242
	v_sub_f32_e32 v91, v91, v242
	v_sub_f32_e32 v92, v92, v242
	v_sub_f32_e32 v93, v93, v242
	v_sub_f32_e32 v94, v94, v242
	v_sub_f32_e32 v95, v95, v242
	v_sub_f32_e32 v64, v64, v242
	v_sub_f32_e32 v65, v65, v242
	v_sub_f32_e32 v66, v66, v242
	v_sub_f32_e32 v67, v67, v242
	v_sub_f32_e32 v68, v68, v242
	v_sub_f32_e32 v69, v69, v242
	v_sub_f32_e32 v70, v70, v242
	v_sub_f32_e32 v71, v71, v242
	v_sub_f32_e32 v72, v72, v242
	v_sub_f32_e32 v73, v73, v242
	v_sub_f32_e32 v74, v74, v242
	v_sub_f32_e32 v75, v75, v242
	v_sub_f32_e32 v76, v76, v242
	v_sub_f32_e32 v77, v77, v242
	v_sub_f32_e32 v78, v78, v242
	v_sub_f32_e32 v79, v79, v242
	v_sub_f32_e32 v226, v226, v242
	v_sub_f32_e32 v227, v227, v242
	v_sub_f32_e32 v228, v228, v242
	v_sub_f32_e32 v229, v229, v242
	v_sub_f32_e32 v230, v230, v242
	v_sub_f32_e32 v231, v231, v242
	v_sub_f32_e32 v232, v232, v242
	v_sub_f32_e32 v233, v233, v242
	v_sub_f32_e32 v234, v234, v242
	v_sub_f32_e32 v235, v235, v242
	v_sub_f32_e32 v236, v236, v242
	v_sub_f32_e32 v237, v237, v242
	v_sub_f32_e32 v238, v238, v242
	v_sub_f32_e32 v239, v239, v242
	v_sub_f32_e32 v240, v240, v242
	v_sub_f32_e32 v241, v241, v242
	s_branch .LBB0_131

; __device__ __forceinline__ void finishSM(f32x16& p0, f32x16& p1, float alpha, float& l_reg, bf16x8& pa0, bf16x8& pa1, bf16x8& pa2, bf16x8& pa3) {
; #pragma unroll
;   for (int r = 0; r < 16; ++r) p1[r] = __builtin_amdgcn_exp2f(p1[r]);
;   float ps = 0;
; #pragma unroll
;   for (int r = 0; r < 16; ++r) ps += p0[r];
; #pragma unroll
;   for (int r = 0; r < 16; ++r) ps += p1[r];
;   { auto rr = __builtin_amdgcn_permlane32_swap(__float_as_uint(ps), __float_as_uint(ps), false, false);
;     ps = __uint_as_float(rr[0]) + __uint_as_float(rr[1]); }
;   l_reg = l_reg * alpha + ps;
;     ...
;   PK4(p0, 0, pa0); PK4(p0, 8, pa1); PK4(p1, 0, pa2); PK4(p1, 8, pa3);
;     ...
; }
; template <int BUFOFF>
; __device__ __forceinline__ void qkt_diff(f32x16& p0, f32x16& p1, const int* ka, const bf16x8* qr) {
;   typedef __attribute__((address_space(3))) const bf16x8* lp;
;   p0 = f32x16{}; p1 = f32x16{};
; #pragma unroll
;   for (int d0 = 0; d0 < 4; ++d0) {
;     const int a = ka[d0] + BUFOFF;
;     const bf16x8 b0 = *(lp)(a), b1 = *(lp)(a + 8192);
;     p0 = __builtin_amdgcn_mfma_f32_32x32x16_bf16(b0, qr[d0], p0, 0, 0, 0);
;     p1 = __builtin_amdgcn_mfma_f32_32x32x16_bf16(b1, qr[d0], p1, 0, 0, 0);
;   }
; }
.LBB0_131:
	v_exp_f32_e32 v125, v64
	v_exp_f32_e32 v126, v65
	v_exp_f32_e32 v127, v66
	v_exp_f32_e32 v128, v67
	v_exp_f32_e32 v129, v68
	v_exp_f32_e32 v143, v69
	v_exp_f32_e32 v144, v70
	v_exp_f32_e32 v145, v71
	v_exp_f32_e32 v146, v72
	v_exp_f32_e32 v147, v73
	v_exp_f32_e32 v148, v74
	v_exp_f32_e32 v149, v75
	v_exp_f32_e32 v150, v76
	v_exp_f32_e32 v151, v80
	v_exp_f32_e32 v152, v81
	v_exp_f32_e32 v153, v82
	v_exp_f32_e32 v154, v83
	v_exp_f32_e32 v155, v84
	v_exp_f32_e32 v156, v85
	v_exp_f32_e32 v158, v86
	v_exp_f32_e32 v159, v87
	v_exp_f32_e32 v162, v88
	v_exp_f32_e32 v167, v89
	v_exp_f32_e32 v169, v90
	v_exp_f32_e32 v170, v91
	v_exp_f32_e32 v171, v92
	v_exp_f32_e32 v172, v93
	v_exp_f32_e32 v173, v94
	v_exp_f32_e32 v188, v95
	v_exp_f32_e32 v189, v77
	v_exp_f32_e32 v190, v78
	v_exp_f32_e32 v124, v79
	ds_read_b128 v[64:67], v138
	ds_read_b128 v[68:71], v138 offset:8192
	ds_read_b128 v[112:115], v141
	ds_read_b128 v[120:123], v141 offset:8192
	v_mov_b32_e32 v191, v125
	s_waitcnt lgkmcnt(0)
	v_mfma_f32_32x32x16_bf16 v[80:95], v[64:67], v[108:111], v[226:241]
	v_mfma_f32_32x32x16_bf16 v[64:79], v[68:71], v[108:111], v[226:241]
	v_mov_b32_e32 v192, v124
	v_mfma_f32_32x32x16_bf16 v[80:95], v[112:115], v[104:107], v[80:95]
	v_mfma_f32_32x32x16_bf16 v[64:79], v[120:123], v[104:107], v[64:79]
	ds_read_b128 v[112:115], v140
	ds_read_b128 v[120:123], v140 offset:8192
	s_waitcnt lgkmcnt(0)
	v_mfma_f32_32x32x16_bf16 v[80:95], v[112:115], v[100:103], v[80:95]
	v_mfma_f32_32x32x16_bf16 v[64:79], v[120:123], v[100:103], v[64:79]
	ds_read_b128 v[112:115], v139
	ds_read_b128 v[120:123], v139 offset:8192
	s_waitcnt lgkmcnt(0)
	v_mfma_f32_32x32x16_bf16 v[80:95], v[112:115], v[96:99], v[80:95]
	v_add_f32_e32 v112, v162, v151
	v_add_f32_e32 v243, v167, v152
	v_add_f32_e32 v244, v169, v153
	v_add_f32_e32 v245, v170, v154
	v_add_f32_e32 v246, v171, v155
	v_add_f32_e32 v247, v172, v156
	v_add_f32_e32 v251, v173, v158
	v_add_f32_e32 v252, v188, v159
	v_add_f32_e32 v112, v191, v112
	v_add_f32_e32 v243, v126, v243
	v_add_f32_e32 v244, v127, v244
	v_add_f32_e32 v245, v128, v245
	v_add_f32_e32 v246, v129, v246
	v_add_f32_e32 v247, v143, v247
	v_add_f32_e32 v251, v144, v251
	v_add_f32_e32 v252, v145, v252
	v_add_f32_e32 v112, v146, v112
	v_add_f32_e32 v243, v147, v243
	v_mfma_f32_32x32x16_bf16 v[64:79], v[120:123], v[96:99], v[64:79]
	v_add_f32_e32 v244, v148, v244
	v_add_f32_e32 v245, v149, v245
	v_add_f32_e32 v246, v150, v246
	v_add_f32_e32 v247, v189, v247
	v_add_f32_e32 v251, v190, v251
	v_add_f32_e32 v252, v192, v252
	v_add_f32_e32 v112, v112, v243
	v_add_f32_e32 v244, v244, v245
	v_add_f32_e32 v246, v246, v247
	v_add_f32_e32 v251, v251, v252
	v_add_f32_e32 v112, v112, v244
	v_add_f32_e32 v246, v246, v251
	v_add_f32_e32 v120, v112, v246
	v_mov_b32_e32 v121, v120
	v_cvt_pk_bf16_f32 v112, v151, v152
	v_cvt_pk_bf16_f32 v113, v153, v154
	v_cvt_pk_bf16_f32 v114, v155, v156
	v_cvt_pk_bf16_f32 v115, v158, v159
	s_nop 1
	v_permlane32_swap_b32_e32 v120, v121
	v_cvt_pk_bf16_f32 v122, v162, v167
	v_cvt_pk_bf16_f32 v123, v169, v170
	v_cvt_pk_bf16_f32 v124, v171, v172
	v_cvt_pk_bf16_f32 v125, v173, v188
	v_cvt_pk_bf16_f32 v126, v191, v126
	v_cvt_pk_bf16_f32 v127, v127, v128
	v_cvt_pk_bf16_f32 v128, v129, v143
	v_cvt_pk_bf16_f32 v129, v144, v145
	v_cvt_pk_bf16_f32 v144, v146, v147
	v_cvt_pk_bf16_f32 v145, v148, v149
	v_cvt_pk_bf16_f32 v146, v150, v189
	v_cvt_pk_bf16_f32 v147, v190, v192
	s_nop 0
	s_add_u32 s4, s14, 0x20000
	s_addc_u32 s5, s15, 0
	s_add_u32 s56, s14, 0x2020000
	s_mov_b32 m0, s16
	s_addc_u32 s57, s15, 0
	s_add_i32 s55, s42, s55
	s_nop 0
	global_load_lds_dwordx4 v134, s[4:5]
	s_mov_b32 m0, s17
	s_nop 0
	global_load_lds_dwordx4 v135, s[4:5]
	s_mov_b32 m0, s55
	s_nop 0
	global_load_lds_dwordx4 v136, s[56:57]
	s_add_i32 m0, s55, 0x2000
	s_nop 0
	global_load_lds_dwordx4 v137, s[56:57]
	v_lshl_add_u32 v143, s54, 14, v133
	ds_read_b64_tr_b16 v[148:149], v143 offset:0
	ds_read_b64_tr_b16 v[150:151], v143 offset:0x800
	ds_read_b64_tr_b16 v[152:153], v143 offset:0x1000
	ds_read_b64_tr_b16 v[154:155], v143 offset:0x1800
	ds_read_b64_tr_b16 v[170:171], v143 offset:0x2000
	ds_read_b64_tr_b16 v[172:173], v143 offset:0x2800
	ds_read_b64_tr_b16 v[188:189], v143 offset:0x3000
	ds_read_b64_tr_b16 v[190:191], v143 offset:0x3800
	s_nop 0
	s_waitcnt lgkmcnt(6)
	v_mfma_f32_32x32x16_bf16 v[32:47], v[148:151], v[112:115], v[32:47]
	ds_read_b64_tr_b16 v[148:149], v143 offset:0x200
	ds_read_b64_tr_b16 v[150:151], v143 offset:0xa00
	s_waitcnt lgkmcnt(6)
	v_mfma_f32_32x32x16_bf16 v[32:47], v[152:155], v[122:125], v[32:47]
	ds_read_b64_tr_b16 v[152:153], v143 offset:0x1200
	ds_read_b64_tr_b16 v[154:155], v143 offset:0x1a00
	s_waitcnt lgkmcnt(6)
	v_mfma_f32_32x32x16_bf16 v[32:47], v[170:173], v[126:129], v[32:47]
	ds_read_b64_tr_b16 v[170:171], v143 offset:0x2200
	ds_read_b64_tr_b16 v[172:173], v143 offset:0x2a00
	s_waitcnt lgkmcnt(6)
	v_mfma_f32_32x32x16_bf16 v[32:47], v[188:191], v[144:147], v[32:47]
	ds_read_b64_tr_b16 v[188:189], v143 offset:0x3200
	ds_read_b64_tr_b16 v[190:191], v143 offset:0x3a00
	s_waitcnt lgkmcnt(6)
	v_mfma_f32_32x32x16_bf16 v[48:63], v[148:151], v[112:115], v[48:63]
	ds_read_b64_tr_b16 v[148:149], v143 offset:0x400
	ds_read_b64_tr_b16 v[150:151], v143 offset:0xc00
	s_waitcnt lgkmcnt(6)
	v_mfma_f32_32x32x16_bf16 v[48:63], v[152:155], v[122:125], v[48:63]
	ds_read_b64_tr_b16 v[152:153], v143 offset:0x1400
	ds_read_b64_tr_b16 v[154:155], v143 offset:0x1c00
	s_waitcnt lgkmcnt(6)
	v_mfma_f32_32x32x16_bf16 v[48:63], v[170:173], v[126:129], v[48:63]
	ds_read_b64_tr_b16 v[170:171], v143 offset:0x2400
	ds_read_b64_tr_b16 v[172:173], v143 offset:0x2c00
	s_waitcnt lgkmcnt(6)
; #define SBAR() __builtin_amdgcn_sched_barrier(0)
; template <int MLA>
; __device__ __forceinline__ void partialSM(f32x16& p0, f32x16& p1, float& m_reg, float& mn, float& alpha) {
;     ...
;   float pmax = p0[0];
; #pragma unroll
;   for (int r = 1; r < 16; ++r) pmax = fmaxf(pmax, p0[r]);
; #pragma unroll
;   for (int r = 0; r < 16; ++r) pmax = fmaxf(pmax, p1[r]);
;   { auto rr = __builtin_amdgcn_permlane32_swap(__float_as_uint(pmax), __float_as_uint(pmax), false, false);
;     pmax = fmaxf(__uint_as_float(rr[0]), __uint_as_float(rr[1])); }
;   if (__builtin_expect(__all(pmax - m_reg <= THR / SCALE), 1)) { mn = m_reg; alpha = 1.f; }
;   else { mn = fmaxf(m_reg, pmax); alpha = __builtin_amdgcn_exp2f((m_reg - mn) * C); m_reg = mn; }
;   float mnC = -mn * C;
; #pragma unroll
;   for (int r = 0; r < 16; ++r) p0[r] = fmaf(p0[r], C, mnC);
; #pragma unroll
;   for (int r = 0; r < 16; ++r) p1[r] = fmaf(p1[r], C, mnC);
; #pragma unroll
;   for (int r = 0; r < 16; ++r) p0[r] = __builtin_amdgcn_exp2f(p0[r]);
; }
; template <int D0> __device__ __forceinline__ void pv_one_t(f32x16& od, int vb, bf16x8 pa0, bf16x8 pa1, bf16x8 pa2, bf16x8 pa3) {
;   const s16x4 l0 = tr_read<v_rd_off(D0, 0, 0)>(vb), h0 = tr_read<v_rd_off(D0, 0, 1)>(vb), l1 = tr_read<v_rd_off(D0, 1, 0)>(vb), h1 = tr_read<v_rd_off(D0, 1, 1)>(vb);
;   const s16x4 l2 = tr_read<v_rd_off(D0, 2, 0)>(vb), h2 = tr_read<v_rd_off(D0, 2, 1)>(vb), l3 = tr_read<v_rd_off(D0, 3, 0)>(vb), h3 = tr_read<v_rd_off(D0, 3, 1)>(vb);
;   asm volatile("s_waitcnt lgkmcnt(0)" ::: "memory"); SBAR();
;     ...
;   od = __builtin_amdgcn_mfma_f32_32x32x16_bf16(PK(l0, h0), pa0, od, 0, 0, 0);
;   od = __builtin_amdgcn_mfma_f32_32x32x16_bf16(PK(l1, h1), pa1, od, 0, 0, 0);
;   od = __builtin_amdgcn_mfma_f32_32x32x16_bf16(PK(l2, h2), pa2, od, 0, 0, 0);
;   od = __builtin_amdgcn_mfma_f32_32x32x16_bf16(PK(l3, h3), pa3, od, 0, 0, 0);
;     ...
; }
	v_mfma_f32_32x32x16_bf16 v[48:63], v[188:191], v[144:147], v[48:63]
	ds_read_b64_tr_b16 v[188:189], v143 offset:0x3400
	ds_read_b64_tr_b16 v[190:191], v143 offset:0x3c00
	s_waitcnt lgkmcnt(6)
	v_mfma_f32_32x32x16_bf16 v[16:31], v[148:151], v[112:115], v[16:31]
	ds_read_b64_tr_b16 v[148:149], v143 offset:0x600
	ds_read_b64_tr_b16 v[150:151], v143 offset:0xe00
	s_waitcnt lgkmcnt(6)
	v_mfma_f32_32x32x16_bf16 v[16:31], v[152:155], v[122:125], v[16:31]
	ds_read_b64_tr_b16 v[152:153], v143 offset:0x1600
	ds_read_b64_tr_b16 v[154:155], v143 offset:0x1e00
	s_waitcnt lgkmcnt(6)
	v_mfma_f32_32x32x16_bf16 v[16:31], v[170:173], v[126:129], v[16:31]
	ds_read_b64_tr_b16 v[170:171], v143 offset:0x2600
	ds_read_b64_tr_b16 v[172:173], v143 offset:0x2e00
	s_waitcnt lgkmcnt(6)
	v_mfma_f32_32x32x16_bf16 v[16:31], v[188:191], v[144:147], v[16:31]
	ds_read_b64_tr_b16 v[188:189], v143 offset:0x3600
	ds_read_b64_tr_b16 v[190:191], v143 offset:0x3e00
	s_waitcnt lgkmcnt(6)
	v_mfma_f32_32x32x16_bf16 v[0:15], v[148:151], v[112:115], v[0:15]
	v_max_f32_e32 v112, v80, v81
	v_max3_f32 v112, v112, v82, v83
	v_max3_f32 v112, v112, v84, v85
	v_max3_f32 v112, v112, v86, v87
	v_max3_f32 v112, v112, v88, v89
	v_max3_f32 v112, v112, v90, v91
	v_max3_f32 v112, v112, v92, v93
	s_waitcnt lgkmcnt(4)
	v_mfma_f32_32x32x16_bf16 v[0:15], v[152:155], v[122:125], v[0:15]
	v_max3_f32 v112, v112, v94, v95
	v_max3_f32 v112, v112, v64, v65
	v_max3_f32 v112, v112, v66, v67
	v_max3_f32 v112, v112, v68, v69
	v_max3_f32 v112, v112, v70, v71
	v_max3_f32 v112, v112, v72, v73
	v_max3_f32 v112, v112, v74, v75
	v_max3_f32 v112, v112, v76, v77
	s_waitcnt lgkmcnt(2)
	v_mfma_f32_32x32x16_bf16 v[0:15], v[170:173], v[126:129], v[0:15]
	v_max3_f32 v112, v112, v78, v79
	v_mov_b32_e32 v113, v112
	s_nop 1
	v_permlane32_swap_b32_e32 v112, v113
	v_max_f32_e32 v112, v112, v113
	v_cmp_ge_f32_e32 vcc, s70, v112
	s_waitcnt lgkmcnt(0)
	v_mfma_f32_32x32x16_bf16 v[0:15], v[188:191], v[144:147], v[0:15]
	s_cmp_eq_u64 vcc, exec
	s_waitcnt vmcnt(0) lgkmcnt(0)
	s_barrier
	s_cbranch_scc1 .Lal_c_d2
	v_max_f32_e32 v242, 0, v112
	v_exp_f32_e64 v112, -v242
	s_nop 0
	v_pk_mul_f32 v[46:47], v[46:47], v[112:113] op_sel_hi:[1,0]
	v_pk_mul_f32 v[44:45], v[44:45], v[112:113] op_sel_hi:[1,0]
	v_pk_mul_f32 v[42:43], v[42:43], v[112:113] op_sel_hi:[1,0]
	v_pk_mul_f32 v[40:41], v[40:41], v[112:113] op_sel_hi:[1,0]
	v_pk_mul_f32 v[38:39], v[38:39], v[112:113] op_sel_hi:[1,0]
	v_pk_mul_f32 v[36:37], v[36:37], v[112:113] op_sel_hi:[1,0]
	v_pk_mul_f32 v[34:35], v[34:35], v[112:113] op_sel_hi:[1,0]
	v_pk_mul_f32 v[32:33], v[32:33], v[112:113] op_sel_hi:[1,0]
	v_pk_mul_f32 v[62:63], v[62:63], v[112:113] op_sel_hi:[1,0]
	v_pk_mul_f32 v[60:61], v[60:61], v[112:113] op_sel_hi:[1,0]
	v_pk_mul_f32 v[58:59], v[58:59], v[112:113] op_sel_hi:[1,0]
	v_pk_mul_f32 v[56:57], v[56:57], v[112:113] op_sel_hi:[1,0]
	v_pk_mul_f32 v[54:55], v[54:55], v[112:113] op_sel_hi:[1,0]
	v_pk_mul_f32 v[52:53], v[52:53], v[112:113] op_sel_hi:[1,0]
	v_pk_mul_f32 v[50:51], v[50:51], v[112:113] op_sel_hi:[1,0]
	v_pk_mul_f32 v[48:49], v[48:49], v[112:113] op_sel_hi:[1,0]
	v_pk_mul_f32 v[30:31], v[30:31], v[112:113] op_sel_hi:[1,0]
	v_pk_mul_f32 v[28:29], v[28:29], v[112:113] op_sel_hi:[1,0]
	v_pk_mul_f32 v[26:27], v[26:27], v[112:113] op_sel_hi:[1,0]
	v_pk_mul_f32 v[24:25], v[24:25], v[112:113] op_sel_hi:[1,0]
	v_pk_mul_f32 v[22:23], v[22:23], v[112:113] op_sel_hi:[1,0]
	v_pk_mul_f32 v[20:21], v[20:21], v[112:113] op_sel_hi:[1,0]
	v_pk_mul_f32 v[18:19], v[18:19], v[112:113] op_sel_hi:[1,0]
	v_pk_mul_f32 v[16:17], v[16:17], v[112:113] op_sel_hi:[1,0]
	v_pk_mul_f32 v[14:15], v[14:15], v[112:113] op_sel_hi:[1,0]
	v_pk_mul_f32 v[12:13], v[12:13], v[112:113] op_sel_hi:[1,0]
	v_pk_mul_f32 v[10:11], v[10:11], v[112:113] op_sel_hi:[1,0]
	v_pk_mul_f32 v[8:9], v[8:9], v[112:113] op_sel_hi:[1,0]
	v_pk_mul_f32 v[6:7], v[6:7], v[112:113] op_sel_hi:[1,0]
	v_pk_mul_f32 v[4:5], v[4:5], v[112:113] op_sel_hi:[1,0]
	v_pk_mul_f32 v[2:3], v[2:3], v[112:113] op_sel_hi:[1,0]
	v_pk_mul_f32 v[0:1], v[0:1], v[112:113] op_sel_hi:[1,0]
	v_sub_f32_e32 v80, v80, v242
	v_sub_f32_e32 v81, v81, v242
	v_sub_f32_e32 v82, v82, v242
	v_sub_f32_e32 v83, v83, v242
	v_sub_f32_e32 v84, v84, v242
	v_sub_f32_e32 v85, v85, v242
	v_sub_f32_e32 v86, v86, v242
	v_sub_f32_e32 v87, v87, v242
	v_sub_f32_e32 v88, v88, v242
	v_sub_f32_e32 v89, v89, v242
	v_sub_f32_e32 v90, v90, v242
	v_sub_f32_e32 v91, v91, v242
	v_sub_f32_e32 v92, v92, v242
	v_sub_f32_e32 v93, v93, v242
	v_sub_f32_e32 v94, v94, v242
	v_sub_f32_e32 v95, v95, v242
	v_sub_f32_e32 v64, v64, v242
	v_sub_f32_e32 v65, v65, v242
	v_sub_f32_e32 v66, v66, v242
	v_sub_f32_e32 v67, v67, v242
	v_sub_f32_e32 v68, v68, v242
	v_sub_f32_e32 v69, v69, v242
	v_sub_f32_e32 v70, v70, v242
	v_sub_f32_e32 v71, v71, v242
	v_sub_f32_e32 v72, v72, v242
	v_sub_f32_e32 v73, v73, v242
	v_sub_f32_e32 v74, v74, v242
	v_sub_f32_e32 v75, v75, v242
	v_sub_f32_e32 v76, v76, v242
	v_sub_f32_e32 v77, v77, v242
	v_sub_f32_e32 v78, v78, v242
	v_sub_f32_e32 v79, v79, v242
	v_sub_f32_e32 v226, v226, v242
	v_sub_f32_e32 v227, v227, v242
	v_sub_f32_e32 v228, v228, v242
	v_sub_f32_e32 v229, v229, v242
	v_sub_f32_e32 v230, v230, v242
	v_sub_f32_e32 v231, v231, v242
	v_sub_f32_e32 v232, v232, v242
	v_sub_f32_e32 v233, v233, v242
	v_sub_f32_e32 v234, v234, v242
	v_sub_f32_e32 v235, v235, v242
	v_sub_f32_e32 v236, v236, v242
	v_sub_f32_e32 v237, v237, v242
	v_sub_f32_e32 v238, v238, v242
	v_sub_f32_e32 v239, v239, v242
	v_sub_f32_e32 v240, v240, v242
	v_sub_f32_e32 v241, v241, v242
	s_branch .LBB0_133
